# speedup vs baseline: 1.0250x; 1.0038x over previous
; template <int EPI, int AMAP, int KOFFMODE, int K>
; __device__ __forceinline__ void gemm_phase(unsigned char* smem, const bf16_t* A, int lda, const bf16_t* Bt, int NT, const EpiArgs& ea) {
;     ...
;         f32x16 acc[4][2];
; #pragma unroll
;         for (int i = 0; i < 4; ++i)
; #pragma unroll
;             for (int j = 0; j < 2; ++j)
; #pragma unroll
;                 for (int r = 0; r < 16; ++r) acc[i][j][r] = 0.f;
;         for (int kt = 0; kt < nk; ++kt) {
;             if (kt + 1 < nk) GEMM_DMA(m0, n0, kt + 1, cur ^ 1);
;             else if (have_next) GEMM_DMA(m0n, n0n, 0, cur ^ 1);
;             const unsigned char* Ac = smem + cur * STGB + (wm * 128 + l31) * 128;
;             const unsigned char* Bc = smem + cur * STGB + 32768 + (wn * 64 + l31) * 128;
;             bf16x8 fa[2][4], fb[2][2];
;             fb[0][0] = *(const bf16x8*)(Bc + (((0) ^ yz) & 7) * 16);
;             fb[0][1] = *(const bf16x8*)(Bc + 32 * 128 + (((0) ^ yz) & 7) * 16);
; #pragma unroll
;             for (int i = 0; i < 4; ++i) fa[0][i] = *(const bf16x8*)(Ac + i * 32 * 128 + (((0) ^ yz) & 7) * 16);
; #pragma unroll
;             for (int s = 0; s < 4; ++s) {
;                 if (s < 3) {
;                     const int o_ = (((2 * (s + 1)) ^ yz) & 7) * 16;
;                     fb[(s + 1) & 1][0] = *(const bf16x8*)(Bc + o_);
;                     fb[(s + 1) & 1][1] = *(const bf16x8*)(Bc + 32 * 128 + o_);
; #pragma unroll
;                     for (int i = 0; i < 4; ++i) fa[(s + 1) & 1][i] = *(const bf16x8*)(Ac + i * 32 * 128 + o_);
;                 }
; #pragma unroll
;                 for (int i = 0; i < 4; ++i) {
;                     acc[i][0] = __builtin_amdgcn_mfma_f32_32x32x16_bf16(fa[s & 1][i], fb[s & 1][0], acc[i][0], 0, 0, 0);
;                     acc[i][1] = __builtin_amdgcn_mfma_f32_32x32x16_bf16(fa[s & 1][i], fb[s & 1][1], acc[i][1], 0, 0, 0);
;                 }
;                 __builtin_amdgcn_sched_barrier(0);
;             }
;             if (kt + 1 < nk) asm volatile("s_waitcnt vmcnt(0)" ::: "memory");
;             __builtin_amdgcn_s_barrier();
;             cur ^= 1;
;         }
.LBB0_926:
	v_add_u32_e32 v2, s11, v142
	v_ashrrev_i32_e32 v3, 31, v2
	v_add_u32_e32 v0, s10, v142
	s_movk_i32 s4, 0x1800
	v_lshlrev_b64 v[2:3], 12, v[2:3]
	v_mad_i64_i32 v[136:137], s[4:5], v0, s4, v[130:131]
	v_lshl_add_u64 v[138:139], v[134:135], 0, v[2:3]
	v_mov_b32_e32 v2, 0
	v_readlane_b32 s20, v251, 18
	s_mov_b64 s[4:5], 0
	s_mov_b32 s12, 1
	s_mov_b32 s13, 64
	s_mov_b32 s15, s9
	v_mov_b32_e32 v3, v2
	v_mov_b32_e32 v4, v2
	v_mov_b32_e32 v5, v2
	v_mov_b32_e32 v6, v2
	v_mov_b32_e32 v7, v2
	v_mov_b32_e32 v8, v2
	v_mov_b32_e32 v9, v2
	v_mov_b32_e32 v10, v2
	v_mov_b32_e32 v11, v2
	v_mov_b32_e32 v12, v2
	v_mov_b32_e32 v13, v2
	v_mov_b32_e32 v14, v2
	v_mov_b32_e32 v15, v2
	v_mov_b32_e32 v16, v2
	v_mov_b32_e32 v17, v2
	v_mov_b32_e32 v18, v2
	v_mov_b32_e32 v19, v2
	v_mov_b32_e32 v20, v2
	v_mov_b32_e32 v21, v2
	v_mov_b32_e32 v22, v2
	v_mov_b32_e32 v23, v2
	v_mov_b32_e32 v24, v2
	v_mov_b32_e32 v25, v2
	v_mov_b32_e32 v26, v2
	v_mov_b32_e32 v27, v2
	v_mov_b32_e32 v28, v2
	v_mov_b32_e32 v29, v2
	v_mov_b32_e32 v30, v2
	v_mov_b32_e32 v31, v2
	v_mov_b32_e32 v32, v2
	v_mov_b32_e32 v33, v2
	v_mov_b32_e32 v34, v2
	v_mov_b32_e32 v35, v2
	v_mov_b32_e32 v36, v2
	v_mov_b32_e32 v37, v2
	v_mov_b32_e32 v38, v2
	v_mov_b32_e32 v39, v2
	v_mov_b32_e32 v40, v2
	v_mov_b32_e32 v41, v2
	v_mov_b32_e32 v42, v2
	v_mov_b32_e32 v43, v2
	v_mov_b32_e32 v44, v2
	v_mov_b32_e32 v45, v2
	v_mov_b32_e32 v46, v2
	v_mov_b32_e32 v47, v2
	v_mov_b32_e32 v48, v2
	v_mov_b32_e32 v49, v2
	v_mov_b32_e32 v50, v2
	v_mov_b32_e32 v51, v2
	v_mov_b32_e32 v52, v2
	v_mov_b32_e32 v53, v2
	v_mov_b32_e32 v54, v2
	v_mov_b32_e32 v55, v2
	v_mov_b32_e32 v56, v2
	v_mov_b32_e32 v57, v2
	v_mov_b32_e32 v58, v2
	v_mov_b32_e32 v59, v2
	v_mov_b32_e32 v60, v2
	v_mov_b32_e32 v61, v2
	v_mov_b32_e32 v62, v2
	v_mov_b32_e32 v63, v2
	v_mov_b32_e32 v64, v2
	v_mov_b32_e32 v65, v2
	v_mov_b32_e32 v66, v2
	v_mov_b32_e32 v67, v2
	v_mov_b32_e32 v68, v2
	v_mov_b32_e32 v69, v2
	v_mov_b32_e32 v70, v2
	v_mov_b32_e32 v71, v2
	v_mov_b32_e32 v72, v2
	v_mov_b32_e32 v73, v2
	v_mov_b32_e32 v74, v2
	v_mov_b32_e32 v75, v2
	v_mov_b32_e32 v76, v2
	v_mov_b32_e32 v77, v2
	v_mov_b32_e32 v78, v2
	v_mov_b32_e32 v79, v2
	v_mov_b32_e32 v80, v2
	v_mov_b32_e32 v81, v2
	v_mov_b32_e32 v82, v2
	v_mov_b32_e32 v83, v2
	v_mov_b32_e32 v84, v2
	v_mov_b32_e32 v85, v2
	v_mov_b32_e32 v86, v2
	v_mov_b32_e32 v87, v2
	v_mov_b32_e32 v88, v2
	v_mov_b32_e32 v89, v2
	v_mov_b32_e32 v90, v2
	v_mov_b32_e32 v91, v2
	v_mov_b32_e32 v92, v2
	v_mov_b32_e32 v93, v2
	v_mov_b32_e32 v94, v2
	v_mov_b32_e32 v95, v2
	v_mov_b32_e32 v96, v2
	v_mov_b32_e32 v97, v2
	v_mov_b32_e32 v98, v2
	v_mov_b32_e32 v99, v2
	v_mov_b32_e32 v100, v2
	v_mov_b32_e32 v101, v2
	v_mov_b32_e32 v102, v2
	v_mov_b32_e32 v103, v2
	v_mov_b32_e32 v104, v2
	v_mov_b32_e32 v105, v2
	v_mov_b32_e32 v106, v2
	v_mov_b32_e32 v107, v2
	v_mov_b32_e32 v108, v2
	v_mov_b32_e32 v109, v2
	v_mov_b32_e32 v110, v2
	v_mov_b32_e32 v111, v2
	v_mov_b32_e32 v112, v2
	v_mov_b32_e32 v113, v2
	v_mov_b32_e32 v114, v2
	v_mov_b32_e32 v115, v2
	v_mov_b32_e32 v116, v2
	v_mov_b32_e32 v117, v2
	v_mov_b32_e32 v118, v2
	v_mov_b32_e32 v119, v2
	v_mov_b32_e32 v120, v2
	v_mov_b32_e32 v121, v2
	v_mov_b32_e32 v122, v2
	v_mov_b32_e32 v123, v2
	v_mov_b32_e32 v124, v2
	v_mov_b32_e32 v125, v2
	v_mov_b32_e32 v126, v2
	v_mov_b32_e32 v127, v2
	v_mov_b32_e32 v128, v2
	v_mov_b32_e32 v129, v2
	v_readlane_b32 s21, v251, 19
	s_mov_b64 s[34:35], 0x60000
	s_mov_b64 s[68:69], 0x800080
	s_mov_b64 s[80:81], 0x840080
	s_mov_b64 vcc, 0xc0000
	s_mov_b64 s[78:79], 0x120000
	s_lshl_b32 s28, s15, 16
	v_add3_u32 v155, s28, v150, v149
	v_add_u32_e32 v155, v155, v151
	v_add3_u32 v0, s28, v147, v149
	v_add_u32_e32 v0, v0, v151
	ds_read_b128 v[156:159], v155 offset:32768
	ds_read_b128 v[160:163], v155 offset:36864
	ds_read_b128 v[192:195], v0
	ds_read_b128 v[196:199], v0 offset:4096
	ds_read_b128 v[200:203], v0 offset:8192
	ds_read_b128 v[204:207], v0 offset:12288
.LBB0_927:
	s_lshr_b32 s14, s12, 1
	s_mulk_i32 s14, 0xc0
	s_and_b32 s20, s13, 64
	s_add_i32 s20, s14, s20
	s_mov_b32 s9, s15
	s_lshl_b32 s15, s9, 16
	s_xor_b32 s14, s15, 0x10000
	v_readfirstlane_b32 s28, v143
	s_nop 0
	s_add_u32 s28, s28, s14
	v_add3_u32 v155, s15, v150, v149
	v_add_u32_e32 v155, v155, v152
	v_add3_u32 v0, s15, v147, v149
	v_add_u32_e32 v0, v0, v152
	ds_read_b128 v[208:211], v155 offset:32768
	ds_read_b128 v[212:215], v155 offset:36864
	s_waitcnt lgkmcnt(5)
	v_mfma_f32_32x32x16_bf16 v[114:129], v[192:195], v[156:159], v[114:129]
	s_lshl_b64 s[34:35], s[20:21], 1
	s_mov_b32 m0, s28
	v_lshl_add_u64 v[164:165], v[136:137], 0, s[34:35]
	global_load_lds_dwordx4 v[164:165], off
	v_mfma_f32_32x32x16_bf16 v[98:113], v[192:195], v[160:163], v[98:113]
	s_lshl_b64 s[34:35], s[20:21], 1
	s_add_u32 s34, s34, 0x60000
	s_addc_u32 s35, s35, 0
	s_add_u32 m0, s28, 0x2000
	v_lshl_add_u64 v[164:165], v[136:137], 0, s[34:35]
	global_load_lds_dwordx4 v[164:165], off
	ds_read_b128 v[192:195], v0
	s_waitcnt lgkmcnt(5)
	v_mfma_f32_32x32x16_bf16 v[82:97], v[196:199], v[156:159], v[82:97]
	s_lshl_b64 s[34:35], s[20:21], 1
	s_add_u32 s34, s34, 0xc0000
	s_addc_u32 s35, s35, 0
	s_add_u32 m0, s28, 0x4000
	v_lshl_add_u64 v[164:165], v[136:137], 0, s[34:35]
	global_load_lds_dwordx4 v[164:165], off
	v_mfma_f32_32x32x16_bf16 v[66:81], v[196:199], v[160:163], v[66:81]
	s_lshl_b64 s[34:35], s[20:21], 1
	s_add_u32 s34, s34, 0x120000
	s_addc_u32 s35, s35, 0
	s_add_u32 m0, s28, 0x6000
	v_lshl_add_u64 v[164:165], v[136:137], 0, s[34:35]
	global_load_lds_dwordx4 v[164:165], off
	ds_read_b128 v[196:199], v0 offset:4096
	s_waitcnt lgkmcnt(5)
; template <int EPI, int AMAP, int KOFFMODE, int K>
; __device__ __forceinline__ void gemm_phase(unsigned char* smem, const bf16_t* A, int lda, const bf16_t* Bt, int NT, const EpiArgs& ea) {
;     ...
;         for (int kt = 0; kt < nk; ++kt) {
;             if (kt + 1 < nk) GEMM_DMA(m0, n0, kt + 1, cur ^ 1);
;             else if (have_next) GEMM_DMA(m0n, n0n, 0, cur ^ 1);
;             const unsigned char* Ac = smem + cur * STGB + (wm * 128 + l31) * 128;
;             const unsigned char* Bc = smem + cur * STGB + 32768 + (wn * 64 + l31) * 128;
;             bf16x8 fa[2][4], fb[2][2];
;             fb[0][0] = *(const bf16x8*)(Bc + (((0) ^ yz) & 7) * 16);
;             fb[0][1] = *(const bf16x8*)(Bc + 32 * 128 + (((0) ^ yz) & 7) * 16);
; #pragma unroll
;             for (int i = 0; i < 4; ++i) fa[0][i] = *(const bf16x8*)(Ac + i * 32 * 128 + (((0) ^ yz) & 7) * 16);
; #pragma unroll
;             for (int s = 0; s < 4; ++s) {
;                 if (s < 3) {
;                     const int o_ = (((2 * (s + 1)) ^ yz) & 7) * 16;
;                     fb[(s + 1) & 1][0] = *(const bf16x8*)(Bc + o_);
;                     fb[(s + 1) & 1][1] = *(const bf16x8*)(Bc + 32 * 128 + o_);
; #pragma unroll
;                     for (int i = 0; i < 4; ++i) fa[(s + 1) & 1][i] = *(const bf16x8*)(Ac + i * 32 * 128 + o_);
;                 }
; #pragma unroll
;                 for (int i = 0; i < 4; ++i) {
;                     acc[i][0] = __builtin_amdgcn_mfma_f32_32x32x16_bf16(fa[s & 1][i], fb[s & 1][0], acc[i][0], 0, 0, 0);
;                     acc[i][1] = __builtin_amdgcn_mfma_f32_32x32x16_bf16(fa[s & 1][i], fb[s & 1][1], acc[i][1], 0, 0, 0);
;                 }
;                 __builtin_amdgcn_sched_barrier(0);
;             }
;             if (kt + 1 < nk) asm volatile("s_waitcnt vmcnt(0)" ::: "memory");
;             __builtin_amdgcn_s_barrier();
;             cur ^= 1;
;         }
	v_mfma_f32_32x32x16_bf16 v[50:65], v[200:203], v[156:159], v[50:65]
	s_add_u32 s34, s4, 0x7c0080
	s_addc_u32 s35, s5, 0
	s_add_u32 m0, s28, 0x8000
	v_lshl_add_u64 v[164:165], v[138:139], 0, s[34:35]
	global_load_lds_dwordx4 v[164:165], off
	v_mfma_f32_32x32x16_bf16 v[34:49], v[200:203], v[160:163], v[34:49]
	s_add_u32 s34, s4, s68
	s_addc_u32 s35, s5, s69
	s_add_u32 m0, s28, 0xa000
	v_lshl_add_u64 v[164:165], v[138:139], 0, s[34:35]
	global_load_lds_dwordx4 v[164:165], off
	ds_read_b128 v[200:203], v0 offset:8192
	s_waitcnt lgkmcnt(5)
	v_mfma_f32_32x32x16_bf16 v[18:33], v[204:207], v[156:159], v[18:33]
	s_add_u32 s34, s4, s80
	s_addc_u32 s35, s5, s81
	s_add_u32 m0, s28, 0xc000
	v_lshl_add_u64 v[164:165], v[138:139], 0, s[34:35]
	global_load_lds_dwordx4 v[164:165], off
	v_mfma_f32_32x32x16_bf16 v[2:17], v[204:207], v[160:163], v[2:17]
	s_add_u32 s34, s4, 0x880080
	s_addc_u32 s35, s5, 0
	s_add_u32 m0, s28, 0xe000
	v_lshl_add_u64 v[164:165], v[138:139], 0, s[34:35]
	global_load_lds_dwordx4 v[164:165], off
	ds_read_b128 v[204:207], v0 offset:12288
	v_add3_u32 v155, s15, v150, v149
	v_add_u32_e32 v155, v155, v153
	v_add3_u32 v0, s15, v147, v149
	v_add_u32_e32 v0, v0, v153
	ds_read_b128 v[156:159], v155 offset:32768
	ds_read_b128 v[160:163], v155 offset:36864
	s_waitcnt lgkmcnt(5)
	v_mfma_f32_32x32x16_bf16 v[114:129], v[192:195], v[208:211], v[114:129]
	v_mfma_f32_32x32x16_bf16 v[98:113], v[192:195], v[212:215], v[98:113]
	ds_read_b128 v[192:195], v0
	s_waitcnt lgkmcnt(5)
	v_mfma_f32_32x32x16_bf16 v[82:97], v[196:199], v[208:211], v[82:97]
	v_mfma_f32_32x32x16_bf16 v[66:81], v[196:199], v[212:215], v[66:81]
	ds_read_b128 v[196:199], v0 offset:4096
	s_waitcnt lgkmcnt(5)
	v_mfma_f32_32x32x16_bf16 v[50:65], v[200:203], v[208:211], v[50:65]
	v_mfma_f32_32x32x16_bf16 v[34:49], v[200:203], v[212:215], v[34:49]
	ds_read_b128 v[200:203], v0 offset:8192
	s_waitcnt lgkmcnt(5)
	v_mfma_f32_32x32x16_bf16 v[18:33], v[204:207], v[208:211], v[18:33]
	v_mfma_f32_32x32x16_bf16 v[2:17], v[204:207], v[212:215], v[2:17]
	ds_read_b128 v[204:207], v0 offset:12288
	v_add3_u32 v155, s15, v150, v149
	v_add_u32_e32 v155, v155, v154
	v_add3_u32 v0, s15, v147, v149
	v_add_u32_e32 v0, v0, v154
	ds_read_b128 v[208:211], v155 offset:32768
	ds_read_b128 v[212:215], v155 offset:36864
	s_waitcnt lgkmcnt(5)
	v_mfma_f32_32x32x16_bf16 v[114:129], v[192:195], v[156:159], v[114:129]
	v_mfma_f32_32x32x16_bf16 v[98:113], v[192:195], v[160:163], v[98:113]
	ds_read_b128 v[192:195], v0
	s_waitcnt lgkmcnt(5)
	v_mfma_f32_32x32x16_bf16 v[82:97], v[196:199], v[156:159], v[82:97]
	v_mfma_f32_32x32x16_bf16 v[66:81], v[196:199], v[160:163], v[66:81]
	ds_read_b128 v[196:199], v0 offset:4096
	s_waitcnt lgkmcnt(5)
	v_mfma_f32_32x32x16_bf16 v[50:65], v[200:203], v[156:159], v[50:65]
	v_mfma_f32_32x32x16_bf16 v[34:49], v[200:203], v[160:163], v[34:49]
	ds_read_b128 v[200:203], v0 offset:8192
	s_waitcnt lgkmcnt(5)
	v_mfma_f32_32x32x16_bf16 v[18:33], v[204:207], v[156:159], v[18:33]
	v_mfma_f32_32x32x16_bf16 v[2:17], v[204:207], v[160:163], v[2:17]
	ds_read_b128 v[204:207], v0 offset:12288
	s_waitcnt lgkmcnt(3)
	v_mfma_f32_32x32x16_bf16 v[114:129], v[192:195], v[208:211], v[114:129]
	v_mfma_f32_32x32x16_bf16 v[98:113], v[192:195], v[212:215], v[98:113]
	s_waitcnt lgkmcnt(0)
	s_waitcnt vmcnt(0)
	s_barrier
	v_add3_u32 v155, s14, v150, v149
	v_add_u32_e32 v155, v155, v151
	v_add3_u32 v0, s14, v147, v149
	v_add_u32_e32 v0, v0, v151
	ds_read_b128 v[156:159], v155 offset:32768
	ds_read_b128 v[160:163], v155 offset:36864
	ds_read_b128 v[192:195], v0
	v_mfma_f32_32x32x16_bf16 v[82:97], v[196:199], v[208:211], v[82:97]
	v_mfma_f32_32x32x16_bf16 v[66:81], v[196:199], v[212:215], v[66:81]
	ds_read_b128 v[196:199], v0 offset:4096
	v_mfma_f32_32x32x16_bf16 v[50:65], v[200:203], v[208:211], v[50:65]
	v_mfma_f32_32x32x16_bf16 v[34:49], v[200:203], v[212:215], v[34:49]
	ds_read_b128 v[200:203], v0 offset:8192
	v_mfma_f32_32x32x16_bf16 v[18:33], v[204:207], v[208:211], v[18:33]
	v_mfma_f32_32x32x16_bf16 v[2:17], v[204:207], v[212:215], v[2:17]
	ds_read_b128 v[204:207], v0 offset:12288
	s_xor_b32 s15, s9, 1
	s_add_u32 s4, s4, 0x80
	s_addc_u32 s5, s5, 0
	s_add_i32 s12, s12, 1
	s_add_i32 s13, s13, 64
	s_mov_b64 s[34:35], 0x60000
	s_cmpk_eq_i32 s4, 0xf80
	s_cbranch_scc0 .LBB0_927
	s_waitcnt lgkmcnt(0)
	v_writelane_b32 v251, s20, 18
	s_andn2_b64 vcc, exec, s[2:3]
	s_lshl_b32 s2, s15, 16
	v_writelane_b32 v251, s21, 19
	s_cbranch_vccnz .LBB0_919
	v_add_u32_e32 v0, s8, v142
	s_movk_i32 s3, 0x1800
	v_mad_i64_i32 v[138:139], s[4:5], v0, s3, v[130:131]
	s_xor_b32 s3, s2, 0x10000
	v_add_u32_e32 v136, s7, v142
	v_add_u32_e32 v0, s3, v143
	v_ashrrev_i32_e32 v137, 31, v136
	v_add_u32_e32 v155, 0x8000, v0
	v_readfirstlane_b32 s3, v0
	v_lshlrev_b64 v[136:137], 12, v[136:137]
	s_mov_b32 m0, s3
	v_readfirstlane_b32 s3, v155
	v_add_u32_e32 v155, 0x2000, v0
	v_lshl_add_u64 v[136:137], v[132:133], 0, v[136:137]
	global_load_lds_dwordx4 v[138:139], off
	s_mov_b32 m0, s3
	v_readfirstlane_b32 s3, v155
	v_add_u32_e32 v155, 0xa000, v0
	global_load_lds_dwordx4 v[136:137], off
	v_lshl_add_u64 v[156:157], v[138:139], 0, s[34:35]
	s_mov_b32 m0, s3
	s_mov_b64 s[4:5], 0x40000
	v_readfirstlane_b32 s3, v155
	v_add_u32_e32 v155, 0x4000, v0
	global_load_lds_dwordx4 v[156:157], off
	v_lshl_add_u64 v[156:157], v[136:137], 0, s[4:5]
	s_mov_b32 m0, s3
	s_mov_b64 s[4:5], 0xc0000
	v_readfirstlane_b32 s3, v155
	v_add_u32_e32 v155, 0xc000, v0
	global_load_lds_dwordx4 v[156:157], off
	v_lshl_add_u64 v[156:157], v[138:139], 0, s[4:5]
	s_mov_b32 m0, s3
	s_mov_b64 s[12:13], 0x80000
	v_readfirstlane_b32 s3, v155
	v_add_u32_e32 v155, 0x6000, v0
	global_load_lds_dwordx4 v[156:157], off
	v_lshl_add_u64 v[156:157], v[136:137], 0, s[12:13]
	s_mov_b32 m0, s3
	s_mov_b64 s[12:13], 0x120000
	v_readfirstlane_b32 s3, v155
	v_add_u32_e32 v0, 0xe000, v0
	global_load_lds_dwordx4 v[156:157], off
	v_lshl_add_u64 v[138:139], v[138:139], 0, s[12:13]
	s_mov_b32 m0, s3
	v_readfirstlane_b32 s3, v0
	global_load_lds_dwordx4 v[138:139], off
	v_lshl_add_u64 v[136:137], v[136:137], 0, s[4:5]
	s_mov_b32 m0, s3
	s_nop 0
	global_load_lds_dwordx4 v[136:137], off
	s_branch .LBB0_919
